# P5 seam: row-scale (r2s) block moved after the first operand loads; P4 pre-loop vmcnt(0) dropped
# speedup vs baseline: 1.0037x; 1.0037x over previous
.LBB0_964:
	s_mov_b64 s[36:37], 0x80
	v_lshl_add_u64 v[134:135], v[132:133], 0, s[36:37]
	s_add_i32 m0, s5, 0x18000
	s_mov_b64 s[44:45], 0x40080
	s_waitcnt vmcnt(2)
	s_barrier
	global_load_lds_dwordx4 v[134:135], off
	v_lshl_add_u64 v[134:135], v[132:133], 0, s[44:45]
	s_add_i32 m0, s5, 0x1a000
	s_mov_b64 s[46:47], 0x10080
	global_load_lds_dwordx4 v[134:135], off
	v_lshl_add_u64 v[134:135], v[132:133], 0, s[46:47]
	s_add_i32 m0, s5, 0x1c000
	s_mov_b64 s[50:51], 0x50080
	global_load_lds_dwordx4 v[134:135], off
	v_lshl_add_u64 v[132:133], v[132:133], 0, s[50:51]
	s_add_i32 m0, s5, 0x1e000
	s_cmpk_lt_u32 s39, 0x100
	global_load_lds_dwordx4 v[132:133], off
	v_or_b32_e32 v165, s12, v191
	s_mov_b32 s12, 0x10000
	v_or_b32_e32 v162, s52, v3
	s_cselect_b64 s[52:53], -1, 0
	s_add_i32 s72, s12, 0x100
	s_mov_b32 s12, 0x10800
	v_lshlrev_b32_e32 v132, 7, v162
	s_add_i32 s73, s12, 0x100
	s_mov_b32 s12, 0x14800
	v_or_b32_e32 v133, v132, v192
	v_or_b32_e32 v134, v132, v193
	v_lshl_or_b32 v132, s3, 12, v172
	s_waitcnt vmcnt(4)
	s_add_i32 s79, s12, 0x100
	s_mov_b32 s12, 0x18800
	v_or_b32_e32 v163, v132, v192
	v_or_b32_e32 v164, v132, v193
	s_mov_b32 s14, 0x18000
	s_mov_b32 s15, 0x1c000
	v_mov_b32_e32 v132, 0
	v_add_u32_e32 v166, 0x100, v133
	s_add_i32 s80, s12, 0x100
	s_mov_b32 s12, 0x1c800
	s_movk_i32 s56, 0xc040
	v_mbcnt_lo_u32_b32 v133, -1, 0
	v_cmp_gt_u32_e64 s[8:9], 8, v3
	s_mov_b32 s55, 0
	v_cmp_eq_u32_e64 s[10:11], 0, v190
	s_ashr_i32 s39, s2, 31
	v_add_u32_e32 v142, v194, v186
	v_mov_b32_e32 v143, v132
	s_add_i32 s77, s13, 0x100
	v_add_u32_e32 v167, 0x100, v134
	s_add_i32 s81, s12, 0x100
	s_mov_b32 s57, -1
	s_mov_b64 s[58:59], 0x4040
	v_mbcnt_hi_u32_b32 v168, -1, v133
	v_mov_b64_e32 v[144:145], 0x100
	v_mov_b64_e32 v[146:147], 0xff
	s_add_i32 s82, s14, 0x100
	s_add_i32 s83, s15, 0x100
	s_mov_b32 s84, 0
	s_barrier
	s_branch .LBB0_966

.LBB0_1113:
	s_andn2_b64 vcc, exec, s[4:5]
	s_cbranch_vccnz .LBB0_1158
	s_mov_b64 s[98:99], s[0:1]
	s_cmpk_lt_i32 s2, 0x400
	s_cselect_b64 s[0:1], -1, 0
	s_cmpk_gt_i32 s2, 0x3ff
	v_readfirstlane_b32 s10, v156
	s_cbranch_scc1 .LBB0_1122
	s_ashr_i32 s3, s2, 31
	s_lshr_b32 s3, s3, 29
	s_add_i32 s3, s2, s3
	s_and_b32 s4, s3, -8
	s_sub_i32 s11, s2, s4
	s_cmp_gt_i32 s11, -1
	s_cbranch_scc0 .LBB0_1119
	s_lshl_b32 s12, s11, 7
	s_cbranch_execz .LBB0_1120
	s_branch .LBB0_1121

.LBB0_1122:
	s_andn2_b64 vcc, exec, s[0:1]
	s_cbranch_vccnz .LBB0_1158
	s_lshr_b32 s4, s10, 6
	s_ashr_i32 s65, s64, 31
	s_ashr_i32 s67, s66, 31
	s_lshr_b32 s11, s10, 8
	s_lshl_b32 s3, s4, 10
	s_lshl_b64 s[16:17], s[64:65], 19
	s_lshl_b64 s[0:1], s[66:67], 19
	v_readlane_b32 s12, v254, 7
	v_readlane_b32 s13, v254, 8
	s_add_u32 s68, s12, s0
	s_addc_u32 s69, s13, s1
	v_mov_b32_e32 v159, 0
	s_add_i32 s34, s3, 0x100
	v_lshl_add_u64 v[4:5], s[68:69], 0, v[158:159]
	s_add_i32 m0, s34, 0x10000
	s_mov_b64 s[0:1], 0x40000
	global_load_lds_dwordx4 v158, s[68:69]
	v_lshl_add_u64 v[6:7], v[4:5], 0, s[0:1]
	s_add_i32 m0, s34, 0x12000
	s_mov_b64 s[12:13], 0x10000
	global_load_lds_dwordx4 v[6:7], off
	v_lshl_add_u64 v[6:7], v[4:5], 0, s[12:13]
	s_add_i32 m0, s34, 0x14000
	s_mov_b64 s[14:15], 0x50000
	global_load_lds_dwordx4 v[6:7], off
	s_add_i32 m0, s34, 0x16000
	s_add_u32 s26, s42, s16
	v_lshl_add_u64 v[6:7], v[4:5], 0, s[14:15]
	s_addc_u32 s27, s43, s17
	v_mov_b32_e32 v1, v159
	global_load_lds_dwordx4 v[6:7], off
	v_lshl_add_u64 v[6:7], s[26:27], 0, v[0:1]
	s_mov_b32 m0, s34
	s_mov_b64 s[16:17], 0x20000
	s_add_i32 s35, s34, 0x2000
	global_load_lds_dwordx4 v0, s[26:27]
	v_lshl_add_u64 v[8:9], v[6:7], 0, s[16:17]
	s_mov_b32 m0, s35
	s_add_i32 s38, s34, 0x4000
	global_load_lds_dwordx4 v[8:9], off
	v_lshl_add_u64 v[8:9], v[6:7], 0, s[0:1]
	s_mov_b32 m0, s38
	s_mov_b64 s[18:19], 0x60000
	s_add_i32 s39, s34, 0x6000
	global_load_lds_dwordx4 v[8:9], off
	v_lshl_add_u64 v[6:7], v[6:7], 0, s[18:19]
	s_mov_b32 m0, s39
	s_cmp_eq_u32 s11, 1
	global_load_lds_dwordx4 v[6:7], off
	s_mov_b32 s46, 0x10000
	s_cselect_b64 s[20:21], -1, 0
	v_readlane_b32 s100, v254, 0
	v_readlane_b32 s101, v254, 1
	s_and_saveexec_b64 s[94:95], s[100:101]
	s_cbranch_execz .Lp5_r2s_done
	s_ashr_i32 s88, s2, 31
	s_lshr_b32 s88, s88, 29
	s_add_i32 s88, s2, s88
	s_and_b32 s89, s88, 0x1ffff8
	s_ashr_i32 s88, s88, 3
	s_lshr_b32 s90, s88, 29
	s_add_i32 s90, s88, s90
	s_and_b32 s90, s90, 0xfffff8
	s_sub_i32 s89, s2, s89
	s_sub_i32 s88, s88, s90
	s_lshl_b32 s89, s89, 11
	s_lshl_b32 s88, s88, 8
	s_add_i32 s88, s88, s89
	v_or_b32_e32 v204, s88, v156
	v_ashrrev_i32_e32 v205, 31, v204
	v_lshlrev_b64 v[204:205], 6, v[204:205]
	v_lshl_add_u64 v[220:221], s[98:99], 0, v[204:205]
	global_load_dwordx4 v[204:207], v[220:221], off
	global_load_dwordx4 v[208:211], v[220:221], off offset:16
	global_load_dwordx4 v[212:215], v[220:221], off offset:32
	global_load_dwordx4 v[216:219], v[220:221], off offset:48
	v_mov_b32_e32 v200, 0x358637bd
	v_mov_b32_e32 v222, 0x100
	s_waitcnt vmcnt(0)
	v_mov_b32_e32 v220, v205
	v_mov_b32_e32 v221, v206
	v_mov_b32_e32 v205, v207
	v_mov_b32_e32 v206, v209
	v_mov_b32_e32 v207, v210
	v_mov_b32_e32 v209, v211
	v_pk_add_f32 v[204:205], v[220:221], v[204:205]
	v_pk_add_f32 v[206:207], v[206:207], v[208:209]
	v_pk_add_f32 v[204:205], v[204:205], v[204:205] op_sel:[0,1] op_sel_hi:[1,0]
	v_pk_add_f32 v[206:207], v[206:207], v[206:207] op_sel:[0,1] op_sel_hi:[1,0]
	v_add_f32_e32 v210, v212, v213
	v_add_f32_e32 v212, v214, v215
	v_mov_b32_e32 v211, v218
	v_mov_b32_e32 v213, v219
	v_mov_b32_e32 v205, v216
	v_mov_b32_e32 v207, v217
	v_pk_add_f32 v[208:209], v[210:211], v[212:213]
	v_pk_add_f32 v[204:205], v[204:205], v[206:207]
	v_lshl_add_u32 v206, v156, 2, v222
	v_pk_add_f32 v[204:205], v[204:205], v[208:209]
	s_nop 0
	v_add_f32_e32 v204, v204, v205
	v_fmac_f32_e32 v200, 0x3a800000, v204
	v_div_scale_f32 v204, s[92:93], v200, v200, 1.0
	v_rcp_f32_e32 v205, v204
	v_div_scale_f32 v207, vcc, 1.0, v200, 1.0
	v_fma_f32 v208, -v204, v205, 1.0
	v_fmac_f32_e32 v205, v208, v205
	v_mul_f32_e32 v208, v207, v205
	v_fma_f32 v209, -v204, v208, v207
	v_fmac_f32_e32 v208, v209, v205
	v_fma_f32 v204, -v204, v208, v207
	v_div_fmas_f32 v204, v204, v205, v208
	v_div_fixup_f32 v200, v204, v200, 1.0
	v_add_u32_e32 v204, 0x27400, v206
	ds_write_b32 v204, v200
.Lp5_r2s_done:
	s_or_b64 exec, exec, s[94:95]
	s_waitcnt lgkmcnt(0)
	s_barrier
	s_cmp_lg_u32 s11, 1
	s_mov_b32 s44, 0x14000
	s_cbranch_scc1 .LBB0_1125
	s_barrier
